# A2 Neumann steps 1..5: skip the LDS writes of structurally-zero tiles (both ping-pong sets already hold zeros there after A1 / step 0); on top of all8
# speedup vs baseline: 1.0125x; 1.0034x over previous
; __device__ __forceinline__ void rwkv_chunk_group(Frame& F, int bc, unsigned long long& tsub) {
;     ...
;         for (int tt = 0; tt < 8; ++tt) { const float kn = kkv[tt] * __builtin_amdgcn_rsqf(fmaxf(sq[tt], 1e-24f));
;             aa[tt] = -kn; bb[tt] = kn * icv[tt]; vbv[tt] = bq[tt] * vv[tt]; }
;         *(LAS float*)(L + L_GT + (w * 64 + ch) * 4) = run;
;         *(GAS v4u*)(VBp + ch * 64 + tb) = (v4u){pk2(vbv[0], vbv[1]), pk2(vbv[2], vbv[3]), pk2(vbv[4], vbv[5]), pk2(vbv[6], vbv[7])};
;         *(GAS v4u*)(Gp + ch * 64 + tb) = (v4u){pk2(ggv[0], ggv[1]), pk2(ggv[2], ggv[3]), pk2(ggv[4], ggv[5]), pk2(ggv[6], ggv[7])};
;         if (hh + 1 < RW_H) {
;             const bool has = (c * CH + tb > 0);
; #pragma unroll
;             for (int tt = 0; tt < 9; ++tt) { const size_t off = (size_t)(row0 + tb + tt - 1) * PRW + hnext * 64 + ch;
;                 if (tt > 0 || has) { raw[tt][0] = P[off]; raw[tt][1] = P[off + 512]; raw[tt][2] = P[off + 1024]; } }
;         }
;         LBAR();
;         float offs = 0.f, tot = 0.f;
; #pragma unroll
;         for (int g = 0; g < 8; ++g) { const float x = *(const LAS float*)(L + L_GT + (g * 64 + ch) * 4); if (g < w) offs += x; tot += x; }
;         const float etot = __expf(tot);
;         if (w == 0) *(LAS float*)(L + L_WC + ch * 4) = etot;
;         unsigned patt[4], pvt[4], pbh[4], pkh[4]; float hAt = 0.f, hBh = 0.f, hKh = 0.f;
;         float e_ex = __expf(offs);
; #pragma unroll
;         for (int tt = 0; tt < 8; ++tt) { const int t = tb + tt; const float cl = offs + ld[tt];
;             const float e_in = __expf(cl), e_inv = __builtin_amdgcn_rcpf(e_in), e_hat = etot * e_inv;
;             const float At = aa[tt] * e_ex, Bt = bb[tt] * e_inv, Kt = kp[tt] * e_inv, Rt = rr[tt] * e_in, Bh = bb[tt] * e_hat, Kh = kp[tt] * e_hat; e_ex = e_in;
;             *(LAS bf16*)(L + L_AT + t * LD + ch * 2) = (bf16)f2bf(At); *(LAS bf16*)(L + L_BT + t * LD + ch * 2) = (bf16)f2bf(Bt);
;             *(LAS bf16*)(L + L_KT + t * LD + ch * 2) = (bf16)f2bf(Kt); *(LAS bf16*)(L + L_RT + t * LD + ch * 2) = (bf16)f2bf(Rt);
;             if (tt & 1) { patt[tt >> 1] = pk2(hAt, At); pvt[tt >> 1] = pk2(vv[tt - 1], vv[tt]); pbh[tt >> 1] = pk2(hBh, Bh); pkh[tt >> 1] = pk2(hKh, Kh); }
;             hAt = At; hBh = Bh; hKh = Kh;
;         }
;         *(LAS v4u*)(L + L_ATT + ch * LD + tb * 2) = (v4u){patt[0], patt[1], patt[2], patt[3]};
.LBB0_1418:
	v_cndmask_b32_e64 v182, v185, 0, s[82:83]
	v_readlane_b32 s66, v254, 40
	v_add_f32_e32 v47, v47, v182
	v_readlane_b32 s67, v254, 41
	s_or_b64 vcc, s[40:41], s[50:51]
	s_mov_b32 s17, s16
	v_cndmask_b32_e64 v47, v182, v47, s[66:67]
	v_readlane_b32 s66, v254, 42
	v_add_f32_e32 v102, v102, v47
	v_readlane_b32 s67, v254, 43
	s_nop 1
	v_cndmask_b32_e64 v47, v47, v102, s[66:67]
	v_readlane_b32 s66, v254, 44
	v_add_f32_e32 v102, v103, v47
	v_readlane_b32 s67, v254, 45
	s_nop 1
	v_cndmask_b32_e64 v47, v47, v102, s[66:67]
	v_readlane_b32 s66, v254, 46
	v_add_f32_e32 v98, v98, v47
	v_readlane_b32 s67, v254, 47
	s_nop 1
	v_cndmask_b32_e64 v47, v47, v98, s[66:67]
	v_readlane_b32 s66, v254, 48
	v_add_f32_e32 v98, v99, v47
	v_readlane_b32 s67, v254, 49
	v_max_f32_e64 v99, s77, s77
	v_max_f32_e32 v99, 0x179abe15, v99
	v_cndmask_b32_e64 v47, v47, v98, s[66:67]
	v_readlane_b32 s66, v254, 50
	v_max_f32_e64 v98, s71, s71
	v_add_f32_e32 v96, v96, v47
	v_readlane_b32 s67, v254, 51
	v_max_f32_e32 v98, 0x179abe15, v98
	v_rsq_f32_e32 v98, v98
	v_cndmask_b32_e64 v47, v47, v96, s[66:67]
	v_rsq_f32_e32 v99, v99
	v_add_f32_e32 v102, v97, v47
	v_max_f32_e64 v97, s14, s14
	v_readlane_b32 s14, v254, 53
	v_readlane_b32 s15, v254, 54
	v_pk_mul_f32 v[88:89], v[88:89], v[98:99]
	v_max_f32_e64 v98, s69, s69
	v_cndmask_b32_e64 v47, v47, v102, s[14:15]
	v_max_f32_e64 v99, s70, s70
	v_add_f32_e32 v102, v177, v47
	v_max_f32_e32 v98, 0x179abe15, v98
	v_max_f32_e32 v99, 0x179abe15, v99
	v_mul_f32_e32 v102, 0x3fb8aa3b, v102
	v_max_f32_e64 v96, s93, s93
	v_rsq_f32_e32 v98, v98
	v_rsq_f32_e32 v99, v99
	v_exp_f32_e32 v103, v102
	v_max_f32_e32 v96, 0x179abe15, v96
	v_max_f32_e32 v97, 0x179abe15, v97
	v_rsq_f32_e32 v96, v96
	v_rsq_f32_e32 v97, v97
	v_pk_mul_f32 v[98:99], v[80:81], v[98:99]
	v_rcp_f32_e32 v80, v103
	v_mul_f32_e32 v81, 0x3fb8aa3b, v47
	v_pk_mul_f32 v[96:97], v[100:101], v[96:97]
	v_exp_f32_e32 v102, v81
	v_pk_mul_f32 v[38:39], v[38:39], v[96:97]
	s_mul_i32 s14, s16, 0x480
	v_mul_f32_e32 v81, v38, v80
	v_pk_mul_f32 v[186:187], v[86:87], v[98:99]
	v_mul_f32_e32 v86, v40, v80
	v_mul_f32_e32 v87, v173, v103
	v_cvt_pk_bf16_f32 v81, v81, s0
	v_add_u32_e32 v173, s14, v58
	ds_write_b16 v173, v81 offset:9216
	v_cvt_pk_bf16_f32 v81, v86, s0
	v_add_f32_e32 v86, v176, v47
	v_mul_f32_e32 v86, 0x3fb8aa3b, v86
	v_max_f32_e64 v100, s64, s64
	v_max_f32_e64 v101, s65, s65
	v_exp_f32_e32 v176, v86
	v_max_f32_e32 v100, 0x179abe15, v100
	v_max_f32_e32 v101, 0x179abe15, v101
	v_rsq_f32_e32 v100, v100
	v_rsq_f32_e32 v101, v101
	ds_write_b16 v173, v81 offset:18432
	v_cvt_pk_bf16_f32 v81, v87, s0
	ds_write_b16 v173, v81 offset:27648
	v_rcp_f32_e32 v81, v176
	v_pk_mul_f32 v[44:45], v[44:45], v[100:101]
	v_pk_mul_f32 v[86:87], v[102:103], v[96:97] neg_lo:[0,1] neg_hi:[0,1]
	v_pk_mul_f32 v[100:101], v[94:95], v[44:45]
	v_cvt_pk_bf16_f32 v94, v86, s0
	ds_write_b16 v173, v94
	v_mul_f32_e32 v94, v39, v81
	v_mul_f32_e32 v95, v41, v81
	v_cvt_pk_bf16_f32 v94, v94, s0
	v_mul_f32_e32 v96, v174, v176
	ds_write_b16 v173, v94 offset:9360
	v_cvt_pk_bf16_f32 v94, v95, s0
	ds_write_b16 v173, v94 offset:18576
	v_cvt_pk_bf16_f32 v94, v96, s0
	ds_write_b16 v173, v94 offset:27792
	v_add_f32_e32 v94, v179, v47
	v_mul_f32_e32 v94, 0x3fb8aa3b, v94
	v_exp_f32_e32 v177, v94
	v_pk_mul_f32 v[82:83], v[82:83], v[88:89]
	v_pk_mul_f32 v[80:81], v[46:47], v[80:81] op_sel_hi:[0,1]
	v_pk_mul_f32 v[40:41], v[40:41], v[80:81]
	v_rcp_f32_e32 v96, v177
	v_pk_mul_f32 v[94:95], v[38:39], v[80:81]
	v_cvt_pk_bf16_f32 v80, v36, v37
	v_cvt_pk_bf16_f32 v97, v87, s0
	v_mul_f32_e32 v36, v82, v96
	v_cvt_pk_bf16_f32 v36, v36, s0
	ds_write_b16 v173, v36 offset:9504
	v_add_f32_e32 v36, v181, v47
	v_mul_f32_e32 v36, 0x3fb8aa3b, v36
	v_exp_f32_e32 v36, v36
	ds_write_b16 v173, v97 offset:144
	v_mul_f32_e32 v37, v78, v96
	v_mul_f32_e32 v39, v175, v177
	v_rcp_f32_e32 v97, v36
	v_cvt_pk_bf16_f32 v37, v37, s0
	v_cvt_pk_bf16_f32 v38, v86, v87
	v_cvt_pk_bf16_f32 v86, v94, v95
	v_cvt_pk_bf16_f32 v94, v40, v41
	ds_write_b16 v173, v37 offset:18720
	v_cvt_pk_bf16_f32 v37, v39, s0
	v_pk_mul_f32 v[40:41], v[176:177], v[88:89] neg_lo:[0,1] neg_hi:[0,1]
	ds_write_b16 v173, v37 offset:27936
	v_cvt_pk_bf16_f32 v37, v40, s0
	ds_write_b16 v173, v37 offset:288
	v_mul_f32_e32 v37, v83, v97
	v_mul_f32_e32 v39, v79, v97
	v_cvt_pk_bf16_f32 v37, v37, s0
	v_mul_f32_e32 v81, v178, v36
	ds_write_b16 v173, v37 offset:9648
	v_cvt_pk_bf16_f32 v37, v39, s0
	ds_write_b16 v173, v37 offset:18864
	v_cvt_pk_bf16_f32 v37, v81, s0
	ds_write_b16 v173, v37 offset:28080
	v_add_f32_e32 v37, v184, v47
	v_mul_f32_e32 v37, 0x3fb8aa3b, v37
	v_exp_f32_e32 v37, v37
	v_cvt_pk_bf16_f32 v39, v40, v41
	v_cvt_pk_bf16_f32 v87, v41, s0
	v_cvt_pk_bf16_f32 v81, v76, v77
	v_rcp_f32_e32 v40, v37
	v_mul_f32_e32 v77, v180, v37
	v_pk_mul_f32 v[36:37], v[36:37], v[98:99] neg_lo:[0,1] neg_hi:[0,1]
	v_pk_mul_f32 v[88:89], v[46:47], v[96:97] op_sel_hi:[0,1]
	v_mul_f32_e32 v41, v186, v40
	v_mul_f32_e32 v76, v90, v40
	v_cvt_pk_bf16_f32 v41, v41, s0
	ds_write_b16 v173, v41 offset:9792
	v_cvt_pk_bf16_f32 v41, v76, s0
	v_add_f32_e32 v76, v190, v47
	v_mul_f32_e32 v76, 0x3fb8aa3b, v76
	v_exp_f32_e32 v76, v76
	ds_write_b16 v173, v41 offset:19008
	v_cvt_pk_bf16_f32 v41, v77, s0
	ds_write_b16 v173, v41 offset:28224
	v_rcp_f32_e32 v41, v76
	v_cvt_pk_bf16_f32 v77, v36, s0
	v_pk_mul_f32 v[78:79], v[78:79], v[88:89]
	ds_write_b16 v173, v77 offset:576
	v_mul_f32_e32 v77, v187, v41
	v_cvt_pk_bf16_f32 v95, v78, v79
	v_mul_f32_e32 v78, v91, v41
	v_cvt_pk_bf16_f32 v77, v77, s0
	v_mul_f32_e32 v79, v183, v76
	ds_write_b16 v173, v77 offset:9936
	v_cvt_pk_bf16_f32 v77, v78, s0
	ds_write_b16 v173, v77 offset:19152
; #define LAS __attribute__((address_space(3)))
; __device__ __forceinline__ void st4_lds(LAS unsigned char* p, f32x4 v) { v2u w; w.x = pk2(v[0], v[1]); w.y = pk2(v[2], v[3]); *(LAS v2u*)p = w; }
; #define LBAR() asm volatile("s_waitcnt lgkmcnt(0)\n\ts_barrier" ::: "memory")
; #define TSUB(k) do { } while (0)
; __device__ __forceinline__ void rwkv_chunk_group(Frame& F, int bc, unsigned long long& tsub) {
;     ...
;         *(LAS v4u*)(L + L_ATT + ch * LD + tb * 2) = (v4u){patt[0], patt[1], patt[2], patt[3]};
;         *(LAS v4u*)(L + L_VT + ch * LD + tb * 2) = (v4u){pvt[0], pvt[1], pvt[2], pvt[3]};
;         *(LAS v4u*)(L + L_BH + ch * LD + tb * 2) = (v4u){pbh[0], pbh[1], pbh[2], pbh[3]};
;         *(LAS v4u*)(L + L_KH + ch * LD + tb * 2) = (v4u){pkh[0], pkh[1], pkh[2], pkh[3]};
;         LBAR();
;     }
;     TSUB(2);
; #pragma unroll
;     for (int q = 0; q < 2; ++q) { const int tw = 2 * w + q, p0 = 16 * (tw >> 2), q0 = 16 * (tw & 3);
;         f32x4 m = mm_tile(L + L_AT, LD, q0, L + L_BT, LD, p0, 2, Z4, fr, fq);
;         f32x4 nak = mm_tile(L + L_KT, LD, q0, L + L_AT, LD, p0, 2, Z4, fr, fq);
;         f32x4 nrk = mm_tile(L + L_KT, LD, q0, L + L_RT, LD, p0, 2, Z4, fr, fq);
;         f32x4 nrb = mm_tile(L + L_BT, LD, q0, L + L_RT, LD, p0, 2, Z4, fr, fq);
;         f32x4 tt;
;         const int p = p0 + fr;
; #pragma unroll
;         for (int v = 0; v < 4; ++v) { const int qq = q0 + 4 * fq + v;
;             if (!(p < qq)) m[v] = 0.f;
;             if (!(qq < p)) nak[v] = 0.f;
;             if (!(qq <= p)) { nrk[v] = 0.f; nrb[v] = 0.f; }
;             tt[v] = (p == qq) ? 1.f : 0.f; }
;         const int o = p * LD + (q0 + 4 * fq) * 2;
;         st4_lds(L + L_M + o, m); st4t_lds(L + L_MT, p, q0 + 4 * fq, m); st4_lds(L + L_NAK + o, nak); st4_lds(L + L_NRK + o, nrk); st4_lds(L + L_NRB + o, nrb); st4_lds(L + L_TT + o, tt);
;     }
;     LBAR();
	v_cvt_pk_bf16_f32 v77, v79, s0
	ds_write_b16 v173, v77 offset:28368
	v_add_f32_e32 v77, v192, v47
	v_mul_f32_e32 v77, 0x3fb8aa3b, v77
	v_exp_f32_e32 v77, v77
	v_pk_mul_f32 v[40:41], v[46:47], v[40:41] op_sel_hi:[0,1]
	v_pk_mul_f32 v[82:83], v[82:83], v[88:89]
	v_pk_mul_f32 v[78:79], v[90:91], v[40:41]
	v_pk_mul_f32 v[88:89], v[186:187], v[40:41]
	v_cvt_pk_bf16_f32 v40, v36, v37
	v_rcp_f32_e32 v36, v77
	ds_write_b16 v173, v87 offset:432
	v_cvt_pk_bf16_f32 v87, v82, v83
	v_cvt_pk_bf16_f32 v82, v37, s0
	v_mul_f32_e32 v37, v100, v36
	v_mul_f32_e32 v41, v42, v36
	v_cvt_pk_bf16_f32 v37, v37, s0
	ds_write_b16 v173, v37 offset:10080
	v_cvt_pk_bf16_f32 v37, v41, s0
	v_add_f32_e32 v41, v52, v47
	v_mul_f32_e32 v41, 0x3fb8aa3b, v41
	v_exp_f32_e32 v41, v41
	v_cvt_pk_bf16_f32 v96, v78, v79
	v_mul_f32_e32 v78, v188, v77
	ds_write_b16 v173, v37 offset:19296
	v_cvt_pk_bf16_f32 v37, v78, s0
	ds_write_b16 v173, v37 offset:28512
	v_rcp_f32_e32 v37, v41
	v_pk_mul_f32 v[44:45], v[76:77], v[44:45] neg_lo:[0,1] neg_hi:[0,1]
	v_mul_f32_e32 v41, v191, v41
	v_cvt_pk_bf16_f32 v47, v44, s0
	ds_write_b16 v173, v47 offset:864
	v_mul_f32_e32 v47, v101, v37
	v_mul_f32_e32 v52, v43, v37
	v_cvt_pk_bf16_f32 v47, v47, s0
	ds_write_b16 v173, v47 offset:10224
	v_cvt_pk_bf16_f32 v47, v52, s0
	v_cvt_pk_bf16_f32 v41, v41, s0
	v_pk_mul_f32 v[36:37], v[46:47], v[36:37] op_sel_hi:[0,1]
	v_cvt_pk_bf16_f32 v76, v45, s0
	ds_write_b16 v173, v41 offset:28656
	v_pk_mul_f32 v[42:43], v[42:43], v[36:37]
	v_pk_mul_f32 v[36:37], v[100:101], v[36:37]
	v_cvt_pk_bf16_f32 v41, v44, v45
	ds_write_b16 v173, v82 offset:720
	v_cvt_pk_bf16_f32 v82, v84, v85
	v_cvt_pk_bf16_f32 v88, v88, v89
	ds_write_b16 v173, v76 offset:1008
	ds_write_b16 v173, v47 offset:19440
	v_cvt_pk_bf16_f32 v97, v42, v43
	v_cvt_pk_bf16_f32 v89, v36, v37
	v_cvt_pk_bf16_f32 v83, v92, v93
	ds_write_b128 v141, v[38:41] offset:36864
	ds_write_b128 v141, v[80:83] offset:46080
	ds_write_b128 v141, v[86:89] offset:55296
	ds_write_b128 v141, v[94:97] offset:64512
	s_waitcnt lgkmcnt(0)
	s_barrier
	v_add_u32_e32 v76, v106, v110
	v_add_u32_e32 v77, v106, v128
	v_add_u32_e32 v97, 0x12000, v127
	v_add_u32_e32 v98, 0x12000, v129
	ds_read_b128 v[176:179], v76 offset:0
	ds_read_b128 v[224:227], v107 offset:9216
	ds_read_b128 v[184:187], v76 offset:18432
	ds_read_b128 v[232:235], v107 offset:0
	ds_read_b128 v[240:243], v107 offset:27648
	ds_read_b128 v[192:195], v76 offset:9216
	ds_read_b128 v[180:183], v76 offset:64
	ds_read_b128 v[228:231], v107 offset:9280
	ds_read_b128 v[188:191], v76 offset:18496
	ds_read_b128 v[236:239], v107 offset:64
	ds_read_b128 v[244:247], v107 offset:27712
	ds_read_b128 v[196:199], v76 offset:9280
	s_waitcnt lgkmcnt(10)
	v_mfma_f32_16x16x32_bf16 v[78:81], v[176:179], v[224:227], 0
	s_waitcnt lgkmcnt(8)
	v_mfma_f32_16x16x32_bf16 v[82:85], v[184:187], v[232:235], 0
	s_waitcnt lgkmcnt(7)
	v_mfma_f32_16x16x32_bf16 v[86:89], v[184:187], v[240:243], 0
	s_waitcnt lgkmcnt(6)
	v_mfma_f32_16x16x32_bf16 v[90:93], v[192:195], v[240:243], 0
	s_waitcnt lgkmcnt(4)
	v_mfma_f32_16x16x32_bf16 v[78:81], v[180:183], v[228:231], v[78:81]
	s_waitcnt lgkmcnt(2)
	v_mfma_f32_16x16x32_bf16 v[82:85], v[188:191], v[236:239], v[82:85]
	s_waitcnt lgkmcnt(1)
	v_mfma_f32_16x16x32_bf16 v[86:89], v[188:191], v[244:247], v[86:89]
	s_waitcnt lgkmcnt(0)
	v_mfma_f32_16x16x32_bf16 v[90:93], v[196:199], v[244:247], v[90:93]
	ds_read_b128 v[176:179], v77 offset:0
	ds_read_b128 v[184:187], v77 offset:18432
	ds_read_b128 v[192:195], v77 offset:9216
	ds_read_b128 v[180:183], v77 offset:64
	ds_read_b128 v[188:191], v77 offset:18496
	ds_read_b128 v[196:199], v77 offset:9280
	s_nop 1
	v_cndmask_b32_e64 v78, 0, v78, s[48:49]
	v_cndmask_b32_e64 v79, v79, 0, s[50:51]
	v_cndmask_b32_e64 v80, 0, v80, s[52:53]
	v_cndmask_b32_e64 v81, 0, v81, s[54:55]
	v_cndmask_b32_e64 v82, 0, v82, s[50:51]
	v_cndmask_b32_e64 v83, 0, v83, s[40:41]
	v_cndmask_b32_e64 v84, 0, v84, s[38:39]
	v_cndmask_b32_e64 v85, 0, v85, s[36:37]
	v_cndmask_b32_e64 v86, v86, 0, s[48:49]
	v_cndmask_b32_e64 v87, 0, v87, s[50:51]
	v_cndmask_b32_e64 v88, v88, 0, s[52:53]
	v_cndmask_b32_e64 v89, v89, 0, s[54:55]
	v_cndmask_b32_e64 v90, v90, 0, s[48:49]
	v_cndmask_b32_e64 v91, 0, v91, s[50:51]
	v_cndmask_b32_e64 v92, v92, 0, s[52:53]
	v_cndmask_b32_e64 v93, v93, 0, s[54:55]
	v_cvt_pk_bf16_f32 v78, v78, v79
	v_cvt_pk_bf16_f32 v79, v80, v81
	v_cvt_pk_bf16_f32 v82, v82, v83
	v_cvt_pk_bf16_f32 v83, v84, v85
	v_cvt_pk_bf16_f32 v86, v86, v87
	v_cvt_pk_bf16_f32 v87, v88, v89
	v_cvt_pk_bf16_f32 v90, v90, v91
	v_cvt_pk_bf16_f32 v91, v92, v93
	ds_write_b64 v97, v[78:79]
	ds_write_b16 v148, v78
	ds_write_b16_d16_hi v148, v78 offset:144
	ds_write_b16 v148, v79 offset:288
	ds_write_b16_d16_hi v148, v79 offset:432
	ds_write_b64 v97, v[82:83] offset:27648
	ds_write_b64 v97, v[86:87] offset:36864
	ds_write_b64 v97, v[90:91] offset:46080
	ds_write_b64 v97, v[60:61] offset:18432
	s_waitcnt lgkmcnt(14)
	v_mfma_f32_16x16x32_bf16 v[36:39], v[176:179], v[224:227], 0
	s_waitcnt lgkmcnt(13)
	v_mfma_f32_16x16x32_bf16 v[40:43], v[184:187], v[232:235], 0
	s_waitcnt lgkmcnt(13)
	v_mfma_f32_16x16x32_bf16 v[44:47], v[184:187], v[240:243], 0
	s_waitcnt lgkmcnt(12)
	v_mfma_f32_16x16x32_bf16 v[100:103], v[192:195], v[240:243], 0
	s_waitcnt lgkmcnt(11)
	v_mfma_f32_16x16x32_bf16 v[36:39], v[180:183], v[228:231], v[36:39]
	s_waitcnt lgkmcnt(10)
	v_mfma_f32_16x16x32_bf16 v[40:43], v[188:191], v[236:239], v[40:43]
	s_waitcnt lgkmcnt(10)
	v_mfma_f32_16x16x32_bf16 v[44:47], v[188:191], v[244:247], v[44:47]
	s_waitcnt lgkmcnt(9)
	v_mfma_f32_16x16x32_bf16 v[100:103], v[196:199], v[244:247], v[100:103]
	s_nop 7
	v_cndmask_b32_e64 v36, 0, v36, s[56:57]
	v_cndmask_b32_e64 v37, v37, 0, s[58:59]
	v_cndmask_b32_e64 v38, 0, v38, s[60:61]
	v_cndmask_b32_e64 v39, 0, v39, s[62:63]
	v_cndmask_b32_e64 v40, 0, v40, s[58:59]
	v_cndmask_b32_e64 v41, 0, v41, s[46:47]
	v_cndmask_b32_e64 v42, 0, v42, s[44:45]
	v_cndmask_b32_e64 v43, 0, v43, s[42:43]
	v_cndmask_b32_e64 v44, v44, 0, s[56:57]
	v_cndmask_b32_e64 v45, 0, v45, s[58:59]
	v_cndmask_b32_e64 v46, v46, 0, s[60:61]
	v_cndmask_b32_e64 v47, v47, 0, s[62:63]
	v_cndmask_b32_e64 v100, v100, 0, s[56:57]
	v_cndmask_b32_e64 v101, 0, v101, s[58:59]
	v_cndmask_b32_e64 v102, v102, 0, s[60:61]
	v_cndmask_b32_e64 v103, v103, 0, s[62:63]
	v_cvt_pk_bf16_f32 v36, v36, v37
	v_cvt_pk_bf16_f32 v37, v38, v39
	v_cvt_pk_bf16_f32 v40, v40, v41
	v_cvt_pk_bf16_f32 v41, v42, v43
	v_cvt_pk_bf16_f32 v44, v44, v45
	v_cvt_pk_bf16_f32 v45, v46, v47
	v_cvt_pk_bf16_f32 v100, v100, v101
	v_cvt_pk_bf16_f32 v101, v102, v103
	ds_write_b64 v98, v[36:37]
	ds_write_b16 v149, v36
	ds_write_b16_d16_hi v149, v36 offset:144
	ds_write_b16 v149, v37 offset:288
	ds_write_b16_d16_hi v149, v37 offset:432
	ds_write_b64 v98, v[40:41] offset:27648
	ds_write_b64 v98, v[44:45] offset:36864
	ds_write_b64 v98, v[100:101] offset:46080
	ds_write_b64 v98, v[72:73] offset:18432
	s_andn2_b64 vcc, exec, s[78:79]
	s_waitcnt lgkmcnt(0)
	s_barrier
; __device__ __forceinline__ void st4_lds(LAS unsigned char* p, f32x4 v) { v2u w; w.x = pk2(v[0], v[1]); w.y = pk2(v[2], v[3]); *(LAS v2u*)p = w; }
; __device__ __forceinline__ f32x4 ld4_lds(const LAS unsigned char* p) { const v2u w = *(const LAS v2u*)p; return (f32x4){bflo(w.x), bfhi(w.x), bflo(w.y), bfhi(w.y)}; }
; #define LBAR() asm volatile("s_waitcnt lgkmcnt(0)\n\ts_barrier" ::: "memory")
; __device__ __forceinline__ void rwkv_chunk_group(Frame& F, int bc, unsigned long long& tsub) {
;     ...
;     for (int it = 0; it < 6; ++it) {
;         const int rM = (it & 1) ? L_AT : L_M, rMT = (it & 1) ? L_BT : L_MT, rTT = (it & 1) ? L_KT : L_TT;
;         const int wM = (it & 1) ? L_M : L_AT, wMT = (it & 1) ? L_MT : L_BT, wTT = (it & 1) ? L_TT : L_KT;
; #pragma unroll
;         for (int q = 0; q < 2; ++q) { const int tw = 2 * w + q, p0 = 16 * (tw >> 2), q0 = 16 * (tw & 3); const int o = (p0 + fr) * LD + (q0 + 4 * fq) * 2;
;             f32x4 tn = Z4, mn = Z4;
;             if (q0 <= p0) { tn = mm_tile(L + rM, LD, q0, L + rTT, LD, p0, 2, ld4_lds(L + rTT + o), fr, fq);
;                           }
;             if (q0 >= p0 && it < 5) mn = mm_tile(L + rMT, LD, q0, L + rM, LD, p0, 2, Z4, fr, fq);
;             st4_lds(L + wTT + o, tn); if (it < 5) { st4_lds(L + wM + o, mn); st4t_lds(L + wMT, p0 + fr, q0 + 4 * fq, mn); } }
;         LBAR();
;     }
	v_mov_b32_e32 v78, v127
	v_mov_b32_e32 v79, v129
	v_add_u32_e32 v173, v106, v110
	v_add_u32_e32 v174, v106, v128
	v_add_u32_e32 v97, 0x12000, v127
	v_add_u32_e32 v98, 0x12000, v129
	v_mov_b32_e32 v102, 0
	v_mov_b32_e32 v103, 0
	v_add_u32_e32 v175, 0x12000, v173
	v_add_u32_e32 v96, 0x12000, v174
	s_and_b64 vcc, exec, s[78:79]
	s_cbranch_vccz .La2_FTFT
	s_and_b64 vcc, exec, s[84:85]
	s_cbranch_vccz .La2_TFTx
	ds_read_b64 v[242:243], v97 offset:18432
	ds_read_b128 v[176:179], v175 offset:0
	ds_read_b128 v[224:227], v132 offset:18432
	ds_read_b128 v[184:187], v175 offset:9216
	ds_read_b128 v[232:235], v132 offset:0
	ds_read_b128 v[192:195], v96 offset:9216
	ds_read_b128 v[180:183], v175 offset:64
	ds_read_b128 v[228:231], v132 offset:18496
	ds_read_b128 v[188:191], v175 offset:9280
	ds_read_b128 v[236:239], v132 offset:64
	ds_read_b128 v[196:199], v96 offset:9280
	s_waitcnt lgkmcnt(10)
	v_lshlrev_b32_e32 v240, 16, v242
	v_and_b32_e32 v241, 0xffff0000, v242
	v_lshlrev_b32_e32 v242, 16, v243
	v_and_b32_e32 v243, 0xffff0000, v243
	s_nop 1
	s_waitcnt lgkmcnt(8)
	v_mfma_f32_16x16x32_bf16 v[240:243], v[176:179], v[224:227], v[240:243]
	s_waitcnt lgkmcnt(6)
	v_mfma_f32_16x16x32_bf16 v[244:247], v[184:187], v[232:235], 0
	s_waitcnt lgkmcnt(5)
	v_mfma_f32_16x16x32_bf16 v[248:251], v[192:195], v[232:235], 0
	s_waitcnt lgkmcnt(3)
	v_mfma_f32_16x16x32_bf16 v[240:243], v[180:183], v[228:231], v[240:243]
	s_waitcnt lgkmcnt(1)
	v_mfma_f32_16x16x32_bf16 v[244:247], v[188:191], v[236:239], v[244:247]
	s_waitcnt lgkmcnt(0)
	v_mfma_f32_16x16x32_bf16 v[248:251], v[196:199], v[236:239], v[248:251]
	s_nop 7
	v_cvt_pk_bf16_f32 v176, v240, v241
	v_cvt_pk_bf16_f32 v177, v242, v243
	v_cvt_pk_bf16_f32 v184, v244, v245
	v_cvt_pk_bf16_f32 v185, v246, v247
	v_cvt_pk_bf16_f32 v192, v248, v249
	v_cvt_pk_bf16_f32 v193, v250, v251
	ds_write_b64 v127, v[176:177] offset:18432
	ds_write_b64 v127, v[184:185] offset:0
	ds_write_b16 v151, v184 offset:9216
	ds_write_b16_d16_hi v151, v184 offset:9360
	ds_write_b16 v151, v185 offset:9504
	ds_write_b16_d16_hi v151, v185 offset:9648
	ds_write_b64 v129, v[102:103] offset:18432
	ds_write_b64 v129, v[192:193] offset:0
	ds_write_b16 v152, v192 offset:9216
	ds_write_b16_d16_hi v152, v192 offset:9360
	ds_write_b16 v152, v193 offset:9504
	ds_write_b16_d16_hi v152, v193 offset:9648
	s_waitcnt lgkmcnt(0)
	s_barrier
	ds_read_b64 v[242:243], v127 offset:18432
	ds_read_b128 v[176:179], v173 offset:0
	ds_read_b128 v[224:227], v107 offset:18432
	ds_read_b128 v[184:187], v173 offset:9216
	ds_read_b128 v[232:235], v107 offset:0
	ds_read_b128 v[192:195], v174 offset:9216
	ds_read_b128 v[180:183], v173 offset:64
	ds_read_b128 v[228:231], v107 offset:18496
	ds_read_b128 v[188:191], v173 offset:9280
	ds_read_b128 v[236:239], v107 offset:64
	ds_read_b128 v[196:199], v174 offset:9280
	s_waitcnt lgkmcnt(10)
	v_lshlrev_b32_e32 v240, 16, v242
	v_and_b32_e32 v241, 0xffff0000, v242
	v_lshlrev_b32_e32 v242, 16, v243
	v_and_b32_e32 v243, 0xffff0000, v243
	s_nop 1
	s_waitcnt lgkmcnt(8)
	v_mfma_f32_16x16x32_bf16 v[240:243], v[176:179], v[224:227], v[240:243]
	s_waitcnt lgkmcnt(6)
	v_mfma_f32_16x16x32_bf16 v[244:247], v[184:187], v[232:235], 0
	s_waitcnt lgkmcnt(5)
	v_mfma_f32_16x16x32_bf16 v[248:251], v[192:195], v[232:235], 0
	s_waitcnt lgkmcnt(3)
	v_mfma_f32_16x16x32_bf16 v[240:243], v[180:183], v[228:231], v[240:243]
	s_waitcnt lgkmcnt(1)
	v_mfma_f32_16x16x32_bf16 v[244:247], v[188:191], v[236:239], v[244:247]
	s_waitcnt lgkmcnt(0)
	v_mfma_f32_16x16x32_bf16 v[248:251], v[196:199], v[236:239], v[248:251]
	s_nop 7
	v_cvt_pk_bf16_f32 v176, v240, v241
	v_cvt_pk_bf16_f32 v177, v242, v243
	v_cvt_pk_bf16_f32 v184, v244, v245
	v_cvt_pk_bf16_f32 v185, v246, v247
	v_cvt_pk_bf16_f32 v192, v248, v249
	v_cvt_pk_bf16_f32 v193, v250, v251
	ds_write_b64 v97, v[176:177] offset:18432
	ds_write_b64 v97, v[184:185] offset:0
	ds_write_b16 v148, v184 offset:0
	ds_write_b16_d16_hi v148, v184 offset:144
	ds_write_b16 v148, v185 offset:288
	ds_write_b16_d16_hi v148, v185 offset:432
	ds_write_b64 v98, v[192:193] offset:0
	ds_write_b16 v149, v192 offset:0
	ds_write_b16_d16_hi v149, v192 offset:144
	ds_write_b16 v149, v193 offset:288
	ds_write_b16_d16_hi v149, v193 offset:432
	s_waitcnt lgkmcnt(0)
	s_barrier
	ds_read_b64 v[242:243], v97 offset:18432
	ds_read_b128 v[176:179], v175 offset:0
	ds_read_b128 v[224:227], v132 offset:18432
	ds_read_b128 v[184:187], v175 offset:9216
	ds_read_b128 v[232:235], v132 offset:0
	ds_read_b128 v[192:195], v96 offset:9216
	ds_read_b128 v[180:183], v175 offset:64
	ds_read_b128 v[228:231], v132 offset:18496
	ds_read_b128 v[188:191], v175 offset:9280
	ds_read_b128 v[236:239], v132 offset:64
	ds_read_b128 v[196:199], v96 offset:9280
	s_waitcnt lgkmcnt(10)
	v_lshlrev_b32_e32 v240, 16, v242
	v_and_b32_e32 v241, 0xffff0000, v242
	v_lshlrev_b32_e32 v242, 16, v243
	v_and_b32_e32 v243, 0xffff0000, v243
	s_nop 1
	s_waitcnt lgkmcnt(8)
	v_mfma_f32_16x16x32_bf16 v[240:243], v[176:179], v[224:227], v[240:243]
	s_waitcnt lgkmcnt(6)
	v_mfma_f32_16x16x32_bf16 v[244:247], v[184:187], v[232:235], 0
	s_waitcnt lgkmcnt(5)
	v_mfma_f32_16x16x32_bf16 v[248:251], v[192:195], v[232:235], 0
	s_waitcnt lgkmcnt(3)
	v_mfma_f32_16x16x32_bf16 v[240:243], v[180:183], v[228:231], v[240:243]
	s_waitcnt lgkmcnt(1)
	v_mfma_f32_16x16x32_bf16 v[244:247], v[188:191], v[236:239], v[244:247]
	s_waitcnt lgkmcnt(0)
	v_mfma_f32_16x16x32_bf16 v[248:251], v[196:199], v[236:239], v[248:251]
	s_nop 7
	v_cvt_pk_bf16_f32 v176, v240, v241
	v_cvt_pk_bf16_f32 v177, v242, v243
	v_cvt_pk_bf16_f32 v184, v244, v245
	v_cvt_pk_bf16_f32 v185, v246, v247
	v_cvt_pk_bf16_f32 v192, v248, v249
	v_cvt_pk_bf16_f32 v193, v250, v251
	ds_write_b64 v127, v[176:177] offset:18432
	ds_write_b64 v127, v[184:185] offset:0
	ds_write_b16 v151, v184 offset:9216
	ds_write_b16_d16_hi v151, v184 offset:9360
	ds_write_b16 v151, v185 offset:9504
	ds_write_b16_d16_hi v151, v185 offset:9648
	ds_write_b64 v129, v[192:193] offset:0
	ds_write_b16 v152, v192 offset:9216
	ds_write_b16_d16_hi v152, v192 offset:9360
	ds_write_b16 v152, v193 offset:9504
	ds_write_b16_d16_hi v152, v193 offset:9648
	s_waitcnt lgkmcnt(0)
	s_barrier
; __device__ __forceinline__ void st4_lds(LAS unsigned char* p, f32x4 v) { v2u w; w.x = pk2(v[0], v[1]); w.y = pk2(v[2], v[3]); *(LAS v2u*)p = w; }
; __device__ __forceinline__ f32x4 ld4_lds(const LAS unsigned char* p) { const v2u w = *(const LAS v2u*)p; return (f32x4){bflo(w.x), bfhi(w.x), bflo(w.y), bfhi(w.y)}; }
; #define LBAR() asm volatile("s_waitcnt lgkmcnt(0)\n\ts_barrier" ::: "memory")
; __device__ __forceinline__ void rwkv_chunk_group(Frame& F, int bc, unsigned long long& tsub) {
;     ...
;     for (int it = 0; it < 6; ++it) {
;         const int rM = (it & 1) ? L_AT : L_M, rMT = (it & 1) ? L_BT : L_MT, rTT = (it & 1) ? L_KT : L_TT;
;         const int wM = (it & 1) ? L_M : L_AT, wMT = (it & 1) ? L_MT : L_BT, wTT = (it & 1) ? L_TT : L_KT;
; #pragma unroll
;         for (int q = 0; q < 2; ++q) { const int tw = 2 * w + q, p0 = 16 * (tw >> 2), q0 = 16 * (tw & 3); const int o = (p0 + fr) * LD + (q0 + 4 * fq) * 2;
;             f32x4 tn = Z4, mn = Z4;
;             if (q0 <= p0) { tn = mm_tile(L + rM, LD, q0, L + rTT, LD, p0, 2, ld4_lds(L + rTT + o), fr, fq);
;                           }
;             if (q0 >= p0 && it < 5) mn = mm_tile(L + rMT, LD, q0, L + rM, LD, p0, 2, Z4, fr, fq);
;             st4_lds(L + wTT + o, tn); if (it < 5) { st4_lds(L + wM + o, mn); st4t_lds(L + wMT, p0 + fr, q0 + 4 * fq, mn); } }
;         LBAR();
;     }
	ds_read_b64 v[242:243], v127 offset:18432
	ds_read_b128 v[176:179], v173 offset:0
	ds_read_b128 v[224:227], v107 offset:18432
	ds_read_b128 v[184:187], v173 offset:9216
	ds_read_b128 v[232:235], v107 offset:0
	ds_read_b128 v[192:195], v174 offset:9216
	ds_read_b128 v[180:183], v173 offset:64
	ds_read_b128 v[228:231], v107 offset:18496
	ds_read_b128 v[188:191], v173 offset:9280
	ds_read_b128 v[236:239], v107 offset:64
	ds_read_b128 v[196:199], v174 offset:9280
	s_waitcnt lgkmcnt(10)
	v_lshlrev_b32_e32 v240, 16, v242
	v_and_b32_e32 v241, 0xffff0000, v242
	v_lshlrev_b32_e32 v242, 16, v243
	v_and_b32_e32 v243, 0xffff0000, v243
	s_nop 1
	s_waitcnt lgkmcnt(8)
	v_mfma_f32_16x16x32_bf16 v[240:243], v[176:179], v[224:227], v[240:243]
	s_waitcnt lgkmcnt(6)
	v_mfma_f32_16x16x32_bf16 v[244:247], v[184:187], v[232:235], 0
	s_waitcnt lgkmcnt(5)
	v_mfma_f32_16x16x32_bf16 v[248:251], v[192:195], v[232:235], 0
	s_waitcnt lgkmcnt(3)
	v_mfma_f32_16x16x32_bf16 v[240:243], v[180:183], v[228:231], v[240:243]
	s_waitcnt lgkmcnt(1)
	v_mfma_f32_16x16x32_bf16 v[244:247], v[188:191], v[236:239], v[244:247]
	s_waitcnt lgkmcnt(0)
	v_mfma_f32_16x16x32_bf16 v[248:251], v[196:199], v[236:239], v[248:251]
	s_nop 7
	v_cvt_pk_bf16_f32 v176, v240, v241
	v_cvt_pk_bf16_f32 v177, v242, v243
	v_cvt_pk_bf16_f32 v184, v244, v245
	v_cvt_pk_bf16_f32 v185, v246, v247
	v_cvt_pk_bf16_f32 v192, v248, v249
	v_cvt_pk_bf16_f32 v193, v250, v251
	ds_write_b64 v97, v[176:177] offset:18432
	ds_write_b64 v97, v[184:185] offset:0
	ds_write_b16 v148, v184 offset:0
	ds_write_b16_d16_hi v148, v184 offset:144
	ds_write_b16 v148, v185 offset:288
	ds_write_b16_d16_hi v148, v185 offset:432
	ds_write_b64 v98, v[192:193] offset:0
	ds_write_b16 v149, v192 offset:0
	ds_write_b16_d16_hi v149, v192 offset:144
	ds_write_b16 v149, v193 offset:288
	ds_write_b16_d16_hi v149, v193 offset:432
	s_waitcnt lgkmcnt(0)
	s_barrier
	ds_read_b64 v[242:243], v97 offset:18432
	ds_read_b128 v[176:179], v175 offset:0
	ds_read_b128 v[224:227], v132 offset:18432
	ds_read_b128 v[184:187], v175 offset:9216
	ds_read_b128 v[232:235], v132 offset:0
	ds_read_b128 v[192:195], v96 offset:9216
	ds_read_b128 v[180:183], v175 offset:64
	ds_read_b128 v[228:231], v132 offset:18496
	ds_read_b128 v[188:191], v175 offset:9280
	ds_read_b128 v[236:239], v132 offset:64
	ds_read_b128 v[196:199], v96 offset:9280
	s_waitcnt lgkmcnt(10)
	v_lshlrev_b32_e32 v240, 16, v242
	v_and_b32_e32 v241, 0xffff0000, v242
	v_lshlrev_b32_e32 v242, 16, v243
	v_and_b32_e32 v243, 0xffff0000, v243
	s_nop 1
	s_waitcnt lgkmcnt(8)
	v_mfma_f32_16x16x32_bf16 v[240:243], v[176:179], v[224:227], v[240:243]
	s_waitcnt lgkmcnt(6)
	v_mfma_f32_16x16x32_bf16 v[244:247], v[184:187], v[232:235], 0
	s_waitcnt lgkmcnt(5)
	v_mfma_f32_16x16x32_bf16 v[248:251], v[192:195], v[232:235], 0
	s_waitcnt lgkmcnt(3)
	v_mfma_f32_16x16x32_bf16 v[240:243], v[180:183], v[228:231], v[240:243]
	s_waitcnt lgkmcnt(1)
	v_mfma_f32_16x16x32_bf16 v[244:247], v[188:191], v[236:239], v[244:247]
	s_waitcnt lgkmcnt(0)
	v_mfma_f32_16x16x32_bf16 v[248:251], v[196:199], v[236:239], v[248:251]
	s_nop 7
	v_cvt_pk_bf16_f32 v176, v240, v241
	v_cvt_pk_bf16_f32 v177, v242, v243
	v_cvt_pk_bf16_f32 v184, v244, v245
	v_cvt_pk_bf16_f32 v185, v246, v247
	v_cvt_pk_bf16_f32 v192, v248, v249
	v_cvt_pk_bf16_f32 v193, v250, v251
	ds_write_b64 v127, v[176:177] offset:18432
	ds_write_b64 v127, v[184:185] offset:0
	ds_write_b16 v151, v184 offset:9216
	ds_write_b16_d16_hi v151, v184 offset:9360
	ds_write_b16 v151, v185 offset:9504
	ds_write_b16_d16_hi v151, v185 offset:9648
	ds_write_b64 v129, v[192:193] offset:0
	ds_write_b16 v152, v192 offset:9216
	ds_write_b16_d16_hi v152, v192 offset:9360
	ds_write_b16 v152, v193 offset:9504
	ds_write_b16_d16_hi v152, v193 offset:9648
	s_waitcnt lgkmcnt(0)
	s_barrier
	ds_read_b64 v[242:243], v127 offset:18432
	ds_read_b128 v[176:179], v173 offset:0
	ds_read_b128 v[224:227], v107 offset:18432
	ds_read_b128 v[180:183], v173 offset:64
	ds_read_b128 v[228:231], v107 offset:18496
	s_waitcnt lgkmcnt(4)
	v_lshlrev_b32_e32 v240, 16, v242
	v_and_b32_e32 v241, 0xffff0000, v242
	v_lshlrev_b32_e32 v242, 16, v243
	v_and_b32_e32 v243, 0xffff0000, v243
	s_nop 1
	s_waitcnt lgkmcnt(2)
	v_mfma_f32_16x16x32_bf16 v[240:243], v[176:179], v[224:227], v[240:243]
	s_waitcnt lgkmcnt(0)
	v_mfma_f32_16x16x32_bf16 v[240:243], v[180:183], v[228:231], v[240:243]
	s_nop 7
	v_cvt_pk_bf16_f32 v176, v240, v241
	v_cvt_pk_bf16_f32 v177, v242, v243
	ds_write_b64 v97, v[176:177] offset:18432
	s_waitcnt lgkmcnt(0)
	s_barrier
	s_branch .La2_done
; __device__ __forceinline__ void st4_lds(LAS unsigned char* p, f32x4 v) { v2u w; w.x = pk2(v[0], v[1]); w.y = pk2(v[2], v[3]); *(LAS v2u*)p = w; }
; __device__ __forceinline__ f32x4 ld4_lds(const LAS unsigned char* p) { const v2u w = *(const LAS v2u*)p; return (f32x4){bflo(w.x), bfhi(w.x), bflo(w.y), bfhi(w.y)}; }
; #define LBAR() asm volatile("s_waitcnt lgkmcnt(0)\n\ts_barrier" ::: "memory")
; __device__ __forceinline__ void rwkv_chunk_group(Frame& F, int bc, unsigned long long& tsub) {
;     ...
;     for (int it = 0; it < 6; ++it) {
;         const int rM = (it & 1) ? L_AT : L_M, rMT = (it & 1) ? L_BT : L_MT, rTT = (it & 1) ? L_KT : L_TT;
;         const int wM = (it & 1) ? L_M : L_AT, wMT = (it & 1) ? L_MT : L_BT, wTT = (it & 1) ? L_TT : L_KT;
; #pragma unroll
;         for (int q = 0; q < 2; ++q) { const int tw = 2 * w + q, p0 = 16 * (tw >> 2), q0 = 16 * (tw & 3); const int o = (p0 + fr) * LD + (q0 + 4 * fq) * 2;
;             f32x4 tn = Z4, mn = Z4;
;             if (q0 <= p0) { tn = mm_tile(L + rM, LD, q0, L + rTT, LD, p0, 2, ld4_lds(L + rTT + o), fr, fq);
;                           }
;             if (q0 >= p0 && it < 5) mn = mm_tile(L + rMT, LD, q0, L + rM, LD, p0, 2, Z4, fr, fq);
;             st4_lds(L + wTT + o, tn); if (it < 5) { st4_lds(L + wM + o, mn); st4t_lds(L + wMT, p0 + fr, q0 + 4 * fq, mn); } }
;         LBAR();
;     }
.La2_TFTx:
	s_and_b64 vcc, exec, s[90:91]
	s_cbranch_vccz .La2_TFTF
	ds_read_b64 v[242:243], v97 offset:18432
	ds_read_b64 v[246:247], v98 offset:18432
	ds_read_b128 v[176:179], v175 offset:0
	ds_read_b128 v[224:227], v132 offset:18432
	ds_read_b128 v[184:187], v96 offset:0
	ds_read_b128 v[192:195], v96 offset:9216
	ds_read_b128 v[232:235], v132 offset:0
	ds_read_b128 v[180:183], v175 offset:64
	ds_read_b128 v[228:231], v132 offset:18496
	ds_read_b128 v[188:191], v96 offset:64
	ds_read_b128 v[196:199], v96 offset:9280
	ds_read_b128 v[236:239], v132 offset:64
	s_waitcnt lgkmcnt(11)
	v_lshlrev_b32_e32 v240, 16, v242
	v_and_b32_e32 v241, 0xffff0000, v242
	v_lshlrev_b32_e32 v242, 16, v243
	v_and_b32_e32 v243, 0xffff0000, v243
	s_waitcnt lgkmcnt(10)
	v_lshlrev_b32_e32 v244, 16, v246
	v_and_b32_e32 v245, 0xffff0000, v246
	v_lshlrev_b32_e32 v246, 16, v247
	v_and_b32_e32 v247, 0xffff0000, v247
	s_nop 1
	s_waitcnt lgkmcnt(8)
	v_mfma_f32_16x16x32_bf16 v[240:243], v[176:179], v[224:227], v[240:243]
	s_waitcnt lgkmcnt(7)
	v_mfma_f32_16x16x32_bf16 v[244:247], v[184:187], v[224:227], v[244:247]
	s_waitcnt lgkmcnt(5)
	v_mfma_f32_16x16x32_bf16 v[248:251], v[192:195], v[232:235], 0
	s_waitcnt lgkmcnt(3)
	v_mfma_f32_16x16x32_bf16 v[240:243], v[180:183], v[228:231], v[240:243]
	s_waitcnt lgkmcnt(2)
	v_mfma_f32_16x16x32_bf16 v[244:247], v[188:191], v[228:231], v[244:247]
	s_waitcnt lgkmcnt(0)
	v_mfma_f32_16x16x32_bf16 v[248:251], v[196:199], v[236:239], v[248:251]
	s_nop 7
	v_cvt_pk_bf16_f32 v176, v240, v241
	v_cvt_pk_bf16_f32 v177, v242, v243
	v_cvt_pk_bf16_f32 v184, v244, v245
	v_cvt_pk_bf16_f32 v185, v246, v247
	v_cvt_pk_bf16_f32 v192, v248, v249
	v_cvt_pk_bf16_f32 v193, v250, v251
	ds_write_b64 v127, v[176:177] offset:18432
	ds_write_b64 v127, v[102:103] offset:0
	ds_write_b16 v151, v102 offset:9216
	ds_write_b16_d16_hi v151, v102 offset:9360
	ds_write_b16 v151, v103 offset:9504
	ds_write_b16_d16_hi v151, v103 offset:9648
	ds_write_b64 v129, v[184:185] offset:18432
	ds_write_b64 v129, v[192:193] offset:0
	ds_write_b16 v152, v192 offset:9216
	ds_write_b16_d16_hi v152, v192 offset:9360
	ds_write_b16 v152, v193 offset:9504
	ds_write_b16_d16_hi v152, v193 offset:9648
	s_waitcnt lgkmcnt(0)
	s_barrier
	ds_read_b64 v[242:243], v127 offset:18432
	ds_read_b64 v[246:247], v129 offset:18432
	ds_read_b128 v[176:179], v173 offset:0
	ds_read_b128 v[224:227], v107 offset:18432
	ds_read_b128 v[184:187], v174 offset:0
	ds_read_b128 v[192:195], v174 offset:9216
	ds_read_b128 v[232:235], v107 offset:0
	ds_read_b128 v[180:183], v173 offset:64
	ds_read_b128 v[228:231], v107 offset:18496
	ds_read_b128 v[188:191], v174 offset:64
	ds_read_b128 v[196:199], v174 offset:9280
	ds_read_b128 v[236:239], v107 offset:64
	s_waitcnt lgkmcnt(11)
	v_lshlrev_b32_e32 v240, 16, v242
	v_and_b32_e32 v241, 0xffff0000, v242
	v_lshlrev_b32_e32 v242, 16, v243
	v_and_b32_e32 v243, 0xffff0000, v243
	s_waitcnt lgkmcnt(10)
	v_lshlrev_b32_e32 v244, 16, v246
	v_and_b32_e32 v245, 0xffff0000, v246
	v_lshlrev_b32_e32 v246, 16, v247
	v_and_b32_e32 v247, 0xffff0000, v247
	s_nop 1
	s_waitcnt lgkmcnt(8)
	v_mfma_f32_16x16x32_bf16 v[240:243], v[176:179], v[224:227], v[240:243]
	s_waitcnt lgkmcnt(7)
	v_mfma_f32_16x16x32_bf16 v[244:247], v[184:187], v[224:227], v[244:247]
	s_waitcnt lgkmcnt(5)
	v_mfma_f32_16x16x32_bf16 v[248:251], v[192:195], v[232:235], 0
	s_waitcnt lgkmcnt(3)
	v_mfma_f32_16x16x32_bf16 v[240:243], v[180:183], v[228:231], v[240:243]
	s_waitcnt lgkmcnt(2)
	v_mfma_f32_16x16x32_bf16 v[244:247], v[188:191], v[228:231], v[244:247]
	s_waitcnt lgkmcnt(0)
	v_mfma_f32_16x16x32_bf16 v[248:251], v[196:199], v[236:239], v[248:251]
	s_nop 7
	v_cvt_pk_bf16_f32 v176, v240, v241
	v_cvt_pk_bf16_f32 v177, v242, v243
	v_cvt_pk_bf16_f32 v184, v244, v245
	v_cvt_pk_bf16_f32 v185, v246, v247
	v_cvt_pk_bf16_f32 v192, v248, v249
	v_cvt_pk_bf16_f32 v193, v250, v251
	ds_write_b64 v97, v[176:177] offset:18432
	ds_write_b64 v98, v[184:185] offset:18432
	ds_write_b64 v98, v[192:193] offset:0
	ds_write_b16 v149, v192 offset:0
	ds_write_b16_d16_hi v149, v192 offset:144
	ds_write_b16 v149, v193 offset:288
	ds_write_b16_d16_hi v149, v193 offset:432
	s_waitcnt lgkmcnt(0)
	s_barrier
	ds_read_b64 v[242:243], v97 offset:18432
	ds_read_b64 v[246:247], v98 offset:18432
	ds_read_b128 v[176:179], v175 offset:0
	ds_read_b128 v[224:227], v132 offset:18432
	ds_read_b128 v[184:187], v96 offset:0
	ds_read_b128 v[192:195], v96 offset:9216
	ds_read_b128 v[232:235], v132 offset:0
	ds_read_b128 v[180:183], v175 offset:64
	ds_read_b128 v[228:231], v132 offset:18496
	ds_read_b128 v[188:191], v96 offset:64
	ds_read_b128 v[196:199], v96 offset:9280
	ds_read_b128 v[236:239], v132 offset:64
	s_waitcnt lgkmcnt(11)
	v_lshlrev_b32_e32 v240, 16, v242
	v_and_b32_e32 v241, 0xffff0000, v242
	v_lshlrev_b32_e32 v242, 16, v243
	v_and_b32_e32 v243, 0xffff0000, v243
	s_waitcnt lgkmcnt(10)
	v_lshlrev_b32_e32 v244, 16, v246
	v_and_b32_e32 v245, 0xffff0000, v246
	v_lshlrev_b32_e32 v246, 16, v247
	v_and_b32_e32 v247, 0xffff0000, v247
	s_nop 1
	s_waitcnt lgkmcnt(8)
	v_mfma_f32_16x16x32_bf16 v[240:243], v[176:179], v[224:227], v[240:243]
	s_waitcnt lgkmcnt(7)
	v_mfma_f32_16x16x32_bf16 v[244:247], v[184:187], v[224:227], v[244:247]
	s_waitcnt lgkmcnt(5)
	v_mfma_f32_16x16x32_bf16 v[248:251], v[192:195], v[232:235], 0
	s_waitcnt lgkmcnt(3)
	v_mfma_f32_16x16x32_bf16 v[240:243], v[180:183], v[228:231], v[240:243]
	s_waitcnt lgkmcnt(2)
	v_mfma_f32_16x16x32_bf16 v[244:247], v[188:191], v[228:231], v[244:247]
	s_waitcnt lgkmcnt(0)
	v_mfma_f32_16x16x32_bf16 v[248:251], v[196:199], v[236:239], v[248:251]
	s_nop 7
	v_cvt_pk_bf16_f32 v176, v240, v241
	v_cvt_pk_bf16_f32 v177, v242, v243
	v_cvt_pk_bf16_f32 v184, v244, v245
	v_cvt_pk_bf16_f32 v185, v246, v247
	v_cvt_pk_bf16_f32 v192, v248, v249
	v_cvt_pk_bf16_f32 v193, v250, v251
	ds_write_b64 v127, v[176:177] offset:18432
	ds_write_b64 v129, v[184:185] offset:18432
	ds_write_b64 v129, v[192:193] offset:0
	ds_write_b16 v152, v192 offset:9216
	ds_write_b16_d16_hi v152, v192 offset:9360
	ds_write_b16 v152, v193 offset:9504
	ds_write_b16_d16_hi v152, v193 offset:9648
	s_waitcnt lgkmcnt(0)
	s_barrier
; __device__ __forceinline__ void st4_lds(LAS unsigned char* p, f32x4 v) { v2u w; w.x = pk2(v[0], v[1]); w.y = pk2(v[2], v[3]); *(LAS v2u*)p = w; }
; __device__ __forceinline__ f32x4 ld4_lds(const LAS unsigned char* p) { const v2u w = *(const LAS v2u*)p; return (f32x4){bflo(w.x), bfhi(w.x), bflo(w.y), bfhi(w.y)}; }
; #define LBAR() asm volatile("s_waitcnt lgkmcnt(0)\n\ts_barrier" ::: "memory")
; __device__ __forceinline__ void rwkv_chunk_group(Frame& F, int bc, unsigned long long& tsub) {
;     ...
;     for (int it = 0; it < 6; ++it) {
;         const int rM = (it & 1) ? L_AT : L_M, rMT = (it & 1) ? L_BT : L_MT, rTT = (it & 1) ? L_KT : L_TT;
;         const int wM = (it & 1) ? L_M : L_AT, wMT = (it & 1) ? L_MT : L_BT, wTT = (it & 1) ? L_TT : L_KT;
; #pragma unroll
;         for (int q = 0; q < 2; ++q) { const int tw = 2 * w + q, p0 = 16 * (tw >> 2), q0 = 16 * (tw & 3); const int o = (p0 + fr) * LD + (q0 + 4 * fq) * 2;
;             f32x4 tn = Z4, mn = Z4;
;             if (q0 <= p0) { tn = mm_tile(L + rM, LD, q0, L + rTT, LD, p0, 2, ld4_lds(L + rTT + o), fr, fq);
;                           }
;             if (q0 >= p0 && it < 5) mn = mm_tile(L + rMT, LD, q0, L + rM, LD, p0, 2, Z4, fr, fq);
;             st4_lds(L + wTT + o, tn); if (it < 5) { st4_lds(L + wM + o, mn); st4t_lds(L + wMT, p0 + fr, q0 + 4 * fq, mn); } }
;         LBAR();
;     }
	ds_read_b64 v[242:243], v127 offset:18432
	ds_read_b64 v[246:247], v129 offset:18432
	ds_read_b128 v[176:179], v173 offset:0
	ds_read_b128 v[224:227], v107 offset:18432
	ds_read_b128 v[184:187], v174 offset:0
	ds_read_b128 v[192:195], v174 offset:9216
	ds_read_b128 v[232:235], v107 offset:0
	ds_read_b128 v[180:183], v173 offset:64
	ds_read_b128 v[228:231], v107 offset:18496
	ds_read_b128 v[188:191], v174 offset:64
	ds_read_b128 v[196:199], v174 offset:9280
	ds_read_b128 v[236:239], v107 offset:64
	s_waitcnt lgkmcnt(11)
	v_lshlrev_b32_e32 v240, 16, v242
	v_and_b32_e32 v241, 0xffff0000, v242
	v_lshlrev_b32_e32 v242, 16, v243
	v_and_b32_e32 v243, 0xffff0000, v243
	s_waitcnt lgkmcnt(10)
	v_lshlrev_b32_e32 v244, 16, v246
	v_and_b32_e32 v245, 0xffff0000, v246
	v_lshlrev_b32_e32 v246, 16, v247
	v_and_b32_e32 v247, 0xffff0000, v247
	s_nop 1
	s_waitcnt lgkmcnt(8)
	v_mfma_f32_16x16x32_bf16 v[240:243], v[176:179], v[224:227], v[240:243]
	s_waitcnt lgkmcnt(7)
	v_mfma_f32_16x16x32_bf16 v[244:247], v[184:187], v[224:227], v[244:247]
	s_waitcnt lgkmcnt(5)
	v_mfma_f32_16x16x32_bf16 v[248:251], v[192:195], v[232:235], 0
	s_waitcnt lgkmcnt(3)
	v_mfma_f32_16x16x32_bf16 v[240:243], v[180:183], v[228:231], v[240:243]
	s_waitcnt lgkmcnt(2)
	v_mfma_f32_16x16x32_bf16 v[244:247], v[188:191], v[228:231], v[244:247]
	s_waitcnt lgkmcnt(0)
	v_mfma_f32_16x16x32_bf16 v[248:251], v[196:199], v[236:239], v[248:251]
	s_nop 7
	v_cvt_pk_bf16_f32 v176, v240, v241
	v_cvt_pk_bf16_f32 v177, v242, v243
	v_cvt_pk_bf16_f32 v184, v244, v245
	v_cvt_pk_bf16_f32 v185, v246, v247
	v_cvt_pk_bf16_f32 v192, v248, v249
	v_cvt_pk_bf16_f32 v193, v250, v251
	ds_write_b64 v97, v[176:177] offset:18432
	ds_write_b64 v98, v[184:185] offset:18432
	ds_write_b64 v98, v[192:193] offset:0
	ds_write_b16 v149, v192 offset:0
	ds_write_b16_d16_hi v149, v192 offset:144
	ds_write_b16 v149, v193 offset:288
	ds_write_b16_d16_hi v149, v193 offset:432
	s_waitcnt lgkmcnt(0)
	s_barrier
	ds_read_b64 v[242:243], v97 offset:18432
	ds_read_b64 v[246:247], v98 offset:18432
	ds_read_b128 v[176:179], v175 offset:0
	ds_read_b128 v[224:227], v132 offset:18432
	ds_read_b128 v[184:187], v96 offset:0
	ds_read_b128 v[192:195], v96 offset:9216
	ds_read_b128 v[232:235], v132 offset:0
	ds_read_b128 v[180:183], v175 offset:64
	ds_read_b128 v[228:231], v132 offset:18496
	ds_read_b128 v[188:191], v96 offset:64
	ds_read_b128 v[196:199], v96 offset:9280
	ds_read_b128 v[236:239], v132 offset:64
	s_waitcnt lgkmcnt(11)
	v_lshlrev_b32_e32 v240, 16, v242
	v_and_b32_e32 v241, 0xffff0000, v242
	v_lshlrev_b32_e32 v242, 16, v243
	v_and_b32_e32 v243, 0xffff0000, v243
	s_waitcnt lgkmcnt(10)
	v_lshlrev_b32_e32 v244, 16, v246
	v_and_b32_e32 v245, 0xffff0000, v246
	v_lshlrev_b32_e32 v246, 16, v247
	v_and_b32_e32 v247, 0xffff0000, v247
	s_nop 1
	s_waitcnt lgkmcnt(8)
	v_mfma_f32_16x16x32_bf16 v[240:243], v[176:179], v[224:227], v[240:243]
	s_waitcnt lgkmcnt(7)
	v_mfma_f32_16x16x32_bf16 v[244:247], v[184:187], v[224:227], v[244:247]
	s_waitcnt lgkmcnt(5)
	v_mfma_f32_16x16x32_bf16 v[248:251], v[192:195], v[232:235], 0
	s_waitcnt lgkmcnt(3)
	v_mfma_f32_16x16x32_bf16 v[240:243], v[180:183], v[228:231], v[240:243]
	s_waitcnt lgkmcnt(2)
	v_mfma_f32_16x16x32_bf16 v[244:247], v[188:191], v[228:231], v[244:247]
	s_waitcnt lgkmcnt(0)
	v_mfma_f32_16x16x32_bf16 v[248:251], v[196:199], v[236:239], v[248:251]
	s_nop 7
	v_cvt_pk_bf16_f32 v176, v240, v241
	v_cvt_pk_bf16_f32 v177, v242, v243
	v_cvt_pk_bf16_f32 v184, v244, v245
	v_cvt_pk_bf16_f32 v185, v246, v247
	v_cvt_pk_bf16_f32 v192, v248, v249
	v_cvt_pk_bf16_f32 v193, v250, v251
	ds_write_b64 v127, v[176:177] offset:18432
	ds_write_b64 v129, v[184:185] offset:18432
	ds_write_b64 v129, v[192:193] offset:0
	ds_write_b16 v152, v192 offset:9216
	ds_write_b16_d16_hi v152, v192 offset:9360
	ds_write_b16 v152, v193 offset:9504
	ds_write_b16_d16_hi v152, v193 offset:9648
	s_waitcnt lgkmcnt(0)
	s_barrier
	ds_read_b64 v[242:243], v127 offset:18432
	ds_read_b64 v[246:247], v129 offset:18432
	ds_read_b128 v[176:179], v173 offset:0
	ds_read_b128 v[224:227], v107 offset:18432
	ds_read_b128 v[184:187], v174 offset:0
	ds_read_b128 v[180:183], v173 offset:64
	ds_read_b128 v[228:231], v107 offset:18496
	ds_read_b128 v[188:191], v174 offset:64
	s_waitcnt lgkmcnt(7)
	v_lshlrev_b32_e32 v240, 16, v242
	v_and_b32_e32 v241, 0xffff0000, v242
	v_lshlrev_b32_e32 v242, 16, v243
	v_and_b32_e32 v243, 0xffff0000, v243
	s_waitcnt lgkmcnt(6)
	v_lshlrev_b32_e32 v244, 16, v246
	v_and_b32_e32 v245, 0xffff0000, v246
	v_lshlrev_b32_e32 v246, 16, v247
	v_and_b32_e32 v247, 0xffff0000, v247
	s_nop 1
	s_waitcnt lgkmcnt(4)
	v_mfma_f32_16x16x32_bf16 v[240:243], v[176:179], v[224:227], v[240:243]
	s_waitcnt lgkmcnt(3)
	v_mfma_f32_16x16x32_bf16 v[244:247], v[184:187], v[224:227], v[244:247]
	s_waitcnt lgkmcnt(1)
	v_mfma_f32_16x16x32_bf16 v[240:243], v[180:183], v[228:231], v[240:243]
	s_waitcnt lgkmcnt(0)
	v_mfma_f32_16x16x32_bf16 v[244:247], v[188:191], v[228:231], v[244:247]
	s_nop 7
	v_cvt_pk_bf16_f32 v176, v240, v241
	v_cvt_pk_bf16_f32 v177, v242, v243
	v_cvt_pk_bf16_f32 v184, v244, v245
	v_cvt_pk_bf16_f32 v185, v246, v247
	ds_write_b64 v97, v[176:177] offset:18432
	ds_write_b64 v98, v[184:185] offset:18432
	s_waitcnt lgkmcnt(0)
	s_barrier
	s_branch .La2_done
; __device__ __forceinline__ void st4_lds(LAS unsigned char* p, f32x4 v) { v2u w; w.x = pk2(v[0], v[1]); w.y = pk2(v[2], v[3]); *(LAS v2u*)p = w; }
; __device__ __forceinline__ f32x4 ld4_lds(const LAS unsigned char* p) { const v2u w = *(const LAS v2u*)p; return (f32x4){bflo(w.x), bfhi(w.x), bflo(w.y), bfhi(w.y)}; }
; #define LBAR() asm volatile("s_waitcnt lgkmcnt(0)\n\ts_barrier" ::: "memory")
; __device__ __forceinline__ void rwkv_chunk_group(Frame& F, int bc, unsigned long long& tsub) {
;     ...
;     for (int it = 0; it < 6; ++it) {
;         const int rM = (it & 1) ? L_AT : L_M, rMT = (it & 1) ? L_BT : L_MT, rTT = (it & 1) ? L_KT : L_TT;
;         const int wM = (it & 1) ? L_M : L_AT, wMT = (it & 1) ? L_MT : L_BT, wTT = (it & 1) ? L_TT : L_KT;
; #pragma unroll
;         for (int q = 0; q < 2; ++q) { const int tw = 2 * w + q, p0 = 16 * (tw >> 2), q0 = 16 * (tw & 3); const int o = (p0 + fr) * LD + (q0 + 4 * fq) * 2;
;             f32x4 tn = Z4, mn = Z4;
;             if (q0 <= p0) { tn = mm_tile(L + rM, LD, q0, L + rTT, LD, p0, 2, ld4_lds(L + rTT + o), fr, fq);
;                           }
;             if (q0 >= p0 && it < 5) mn = mm_tile(L + rMT, LD, q0, L + rM, LD, p0, 2, Z4, fr, fq);
;             st4_lds(L + wTT + o, tn); if (it < 5) { st4_lds(L + wM + o, mn); st4t_lds(L + wMT, p0 + fr, q0 + 4 * fq, mn); } }
;         LBAR();
;     }
.La2_TFTF:
	ds_read_b64 v[242:243], v97 offset:18432
	ds_read_b64 v[246:247], v98 offset:18432
	ds_read_b128 v[176:179], v175 offset:0
	ds_read_b128 v[224:227], v132 offset:18432
	ds_read_b128 v[184:187], v96 offset:0
	ds_read_b128 v[180:183], v175 offset:64
	ds_read_b128 v[228:231], v132 offset:18496
	ds_read_b128 v[188:191], v96 offset:64
	s_waitcnt lgkmcnt(7)
	v_lshlrev_b32_e32 v240, 16, v242
	v_and_b32_e32 v241, 0xffff0000, v242
	v_lshlrev_b32_e32 v242, 16, v243
	v_and_b32_e32 v243, 0xffff0000, v243
	s_waitcnt lgkmcnt(6)
	v_lshlrev_b32_e32 v244, 16, v246
	v_and_b32_e32 v245, 0xffff0000, v246
	v_lshlrev_b32_e32 v246, 16, v247
	v_and_b32_e32 v247, 0xffff0000, v247
	s_nop 1
	s_waitcnt lgkmcnt(4)
	v_mfma_f32_16x16x32_bf16 v[240:243], v[176:179], v[224:227], v[240:243]
	s_waitcnt lgkmcnt(3)
	v_mfma_f32_16x16x32_bf16 v[244:247], v[184:187], v[224:227], v[244:247]
	s_waitcnt lgkmcnt(1)
	v_mfma_f32_16x16x32_bf16 v[240:243], v[180:183], v[228:231], v[240:243]
	s_waitcnt lgkmcnt(0)
	v_mfma_f32_16x16x32_bf16 v[244:247], v[188:191], v[228:231], v[244:247]
	s_nop 7
	v_cvt_pk_bf16_f32 v176, v240, v241
	v_cvt_pk_bf16_f32 v177, v242, v243
	v_cvt_pk_bf16_f32 v184, v244, v245
	v_cvt_pk_bf16_f32 v185, v246, v247
	ds_write_b64 v127, v[176:177] offset:18432
	ds_write_b64 v127, v[102:103] offset:0
	ds_write_b16 v151, v102 offset:9216
	ds_write_b16_d16_hi v151, v102 offset:9360
	ds_write_b16 v151, v103 offset:9504
	ds_write_b16_d16_hi v151, v103 offset:9648
	ds_write_b64 v129, v[184:185] offset:18432
	ds_write_b64 v129, v[102:103] offset:0
	ds_write_b16 v152, v102 offset:9216
	ds_write_b16_d16_hi v152, v102 offset:9360
	ds_write_b16 v152, v103 offset:9504
	ds_write_b16_d16_hi v152, v103 offset:9648
	s_waitcnt lgkmcnt(0)
	s_barrier
	ds_read_b64 v[242:243], v127 offset:18432
	ds_read_b64 v[246:247], v129 offset:18432
	ds_read_b128 v[176:179], v173 offset:0
	ds_read_b128 v[224:227], v107 offset:18432
	ds_read_b128 v[184:187], v174 offset:0
	ds_read_b128 v[180:183], v173 offset:64
	ds_read_b128 v[228:231], v107 offset:18496
	ds_read_b128 v[188:191], v174 offset:64
	s_waitcnt lgkmcnt(7)
	v_lshlrev_b32_e32 v240, 16, v242
	v_and_b32_e32 v241, 0xffff0000, v242
	v_lshlrev_b32_e32 v242, 16, v243
	v_and_b32_e32 v243, 0xffff0000, v243
	s_waitcnt lgkmcnt(6)
	v_lshlrev_b32_e32 v244, 16, v246
	v_and_b32_e32 v245, 0xffff0000, v246
	v_lshlrev_b32_e32 v246, 16, v247
	v_and_b32_e32 v247, 0xffff0000, v247
	s_nop 1
	s_waitcnt lgkmcnt(4)
	v_mfma_f32_16x16x32_bf16 v[240:243], v[176:179], v[224:227], v[240:243]
	s_waitcnt lgkmcnt(3)
	v_mfma_f32_16x16x32_bf16 v[244:247], v[184:187], v[224:227], v[244:247]
	s_waitcnt lgkmcnt(1)
	v_mfma_f32_16x16x32_bf16 v[240:243], v[180:183], v[228:231], v[240:243]
	s_waitcnt lgkmcnt(0)
	v_mfma_f32_16x16x32_bf16 v[244:247], v[188:191], v[228:231], v[244:247]
	s_nop 7
	v_cvt_pk_bf16_f32 v176, v240, v241
	v_cvt_pk_bf16_f32 v177, v242, v243
	v_cvt_pk_bf16_f32 v184, v244, v245
	v_cvt_pk_bf16_f32 v185, v246, v247
	ds_write_b64 v97, v[176:177] offset:18432
	ds_write_b64 v98, v[184:185] offset:18432
	s_waitcnt lgkmcnt(0)
	s_barrier
	ds_read_b64 v[242:243], v97 offset:18432
	ds_read_b64 v[246:247], v98 offset:18432
	ds_read_b128 v[176:179], v175 offset:0
	ds_read_b128 v[224:227], v132 offset:18432
	ds_read_b128 v[184:187], v96 offset:0
	ds_read_b128 v[180:183], v175 offset:64
	ds_read_b128 v[228:231], v132 offset:18496
	ds_read_b128 v[188:191], v96 offset:64
	s_waitcnt lgkmcnt(7)
	v_lshlrev_b32_e32 v240, 16, v242
	v_and_b32_e32 v241, 0xffff0000, v242
	v_lshlrev_b32_e32 v242, 16, v243
	v_and_b32_e32 v243, 0xffff0000, v243
	s_waitcnt lgkmcnt(6)
	v_lshlrev_b32_e32 v244, 16, v246
	v_and_b32_e32 v245, 0xffff0000, v246
	v_lshlrev_b32_e32 v246, 16, v247
	v_and_b32_e32 v247, 0xffff0000, v247
	s_nop 1
	s_waitcnt lgkmcnt(4)
	v_mfma_f32_16x16x32_bf16 v[240:243], v[176:179], v[224:227], v[240:243]
	s_waitcnt lgkmcnt(3)
	v_mfma_f32_16x16x32_bf16 v[244:247], v[184:187], v[224:227], v[244:247]
	s_waitcnt lgkmcnt(1)
	v_mfma_f32_16x16x32_bf16 v[240:243], v[180:183], v[228:231], v[240:243]
	s_waitcnt lgkmcnt(0)
	v_mfma_f32_16x16x32_bf16 v[244:247], v[188:191], v[228:231], v[244:247]
	s_nop 7
	v_cvt_pk_bf16_f32 v176, v240, v241
	v_cvt_pk_bf16_f32 v177, v242, v243
	v_cvt_pk_bf16_f32 v184, v244, v245
	v_cvt_pk_bf16_f32 v185, v246, v247
	ds_write_b64 v127, v[176:177] offset:18432
	ds_write_b64 v129, v[184:185] offset:18432
	s_waitcnt lgkmcnt(0)
	s_barrier
	ds_read_b64 v[242:243], v127 offset:18432
	ds_read_b64 v[246:247], v129 offset:18432
	ds_read_b128 v[176:179], v173 offset:0
	ds_read_b128 v[224:227], v107 offset:18432
	ds_read_b128 v[184:187], v174 offset:0
	ds_read_b128 v[180:183], v173 offset:64
	ds_read_b128 v[228:231], v107 offset:18496
	ds_read_b128 v[188:191], v174 offset:64
	s_waitcnt lgkmcnt(7)
	v_lshlrev_b32_e32 v240, 16, v242
	v_and_b32_e32 v241, 0xffff0000, v242
	v_lshlrev_b32_e32 v242, 16, v243
	v_and_b32_e32 v243, 0xffff0000, v243
	s_waitcnt lgkmcnt(6)
	v_lshlrev_b32_e32 v244, 16, v246
	v_and_b32_e32 v245, 0xffff0000, v246
	v_lshlrev_b32_e32 v246, 16, v247
	v_and_b32_e32 v247, 0xffff0000, v247
	s_nop 1
	s_waitcnt lgkmcnt(4)
	v_mfma_f32_16x16x32_bf16 v[240:243], v[176:179], v[224:227], v[240:243]
	s_waitcnt lgkmcnt(3)
	v_mfma_f32_16x16x32_bf16 v[244:247], v[184:187], v[224:227], v[244:247]
	s_waitcnt lgkmcnt(1)
	v_mfma_f32_16x16x32_bf16 v[240:243], v[180:183], v[228:231], v[240:243]
	s_waitcnt lgkmcnt(0)
	v_mfma_f32_16x16x32_bf16 v[244:247], v[188:191], v[228:231], v[244:247]
	s_nop 7
	v_cvt_pk_bf16_f32 v176, v240, v241
	v_cvt_pk_bf16_f32 v177, v242, v243
	v_cvt_pk_bf16_f32 v184, v244, v245
	v_cvt_pk_bf16_f32 v185, v246, v247
	ds_write_b64 v97, v[176:177] offset:18432
	ds_write_b64 v98, v[184:185] offset:18432
	s_waitcnt lgkmcnt(0)
	s_barrier
; __device__ __forceinline__ void st4_lds(LAS unsigned char* p, f32x4 v) { v2u w; w.x = pk2(v[0], v[1]); w.y = pk2(v[2], v[3]); *(LAS v2u*)p = w; }
; __device__ __forceinline__ f32x4 ld4_lds(const LAS unsigned char* p) { const v2u w = *(const LAS v2u*)p; return (f32x4){bflo(w.x), bfhi(w.x), bflo(w.y), bfhi(w.y)}; }
; #define LBAR() asm volatile("s_waitcnt lgkmcnt(0)\n\ts_barrier" ::: "memory")
; __device__ __forceinline__ void rwkv_chunk_group(Frame& F, int bc, unsigned long long& tsub) {
;     ...
;     for (int it = 0; it < 6; ++it) {
;         const int rM = (it & 1) ? L_AT : L_M, rMT = (it & 1) ? L_BT : L_MT, rTT = (it & 1) ? L_KT : L_TT;
;         const int wM = (it & 1) ? L_M : L_AT, wMT = (it & 1) ? L_MT : L_BT, wTT = (it & 1) ? L_TT : L_KT;
; #pragma unroll
;         for (int q = 0; q < 2; ++q) { const int tw = 2 * w + q, p0 = 16 * (tw >> 2), q0 = 16 * (tw & 3); const int o = (p0 + fr) * LD + (q0 + 4 * fq) * 2;
;             f32x4 tn = Z4, mn = Z4;
;             if (q0 <= p0) { tn = mm_tile(L + rM, LD, q0, L + rTT, LD, p0, 2, ld4_lds(L + rTT + o), fr, fq);
;                           }
;             if (q0 >= p0 && it < 5) mn = mm_tile(L + rMT, LD, q0, L + rM, LD, p0, 2, Z4, fr, fq);
;             st4_lds(L + wTT + o, tn); if (it < 5) { st4_lds(L + wM + o, mn); st4t_lds(L + wMT, p0 + fr, q0 + 4 * fq, mn); } }
;         LBAR();
;     }
	ds_read_b64 v[242:243], v97 offset:18432
	ds_read_b64 v[246:247], v98 offset:18432
	ds_read_b128 v[176:179], v175 offset:0
	ds_read_b128 v[224:227], v132 offset:18432
	ds_read_b128 v[184:187], v96 offset:0
	ds_read_b128 v[180:183], v175 offset:64
	ds_read_b128 v[228:231], v132 offset:18496
	ds_read_b128 v[188:191], v96 offset:64
	s_waitcnt lgkmcnt(7)
	v_lshlrev_b32_e32 v240, 16, v242
	v_and_b32_e32 v241, 0xffff0000, v242
	v_lshlrev_b32_e32 v242, 16, v243
	v_and_b32_e32 v243, 0xffff0000, v243
	s_waitcnt lgkmcnt(6)
	v_lshlrev_b32_e32 v244, 16, v246
	v_and_b32_e32 v245, 0xffff0000, v246
	v_lshlrev_b32_e32 v246, 16, v247
	v_and_b32_e32 v247, 0xffff0000, v247
	s_nop 1
	s_waitcnt lgkmcnt(4)
	v_mfma_f32_16x16x32_bf16 v[240:243], v[176:179], v[224:227], v[240:243]
	s_waitcnt lgkmcnt(3)
	v_mfma_f32_16x16x32_bf16 v[244:247], v[184:187], v[224:227], v[244:247]
	s_waitcnt lgkmcnt(1)
	v_mfma_f32_16x16x32_bf16 v[240:243], v[180:183], v[228:231], v[240:243]
	s_waitcnt lgkmcnt(0)
	v_mfma_f32_16x16x32_bf16 v[244:247], v[188:191], v[228:231], v[244:247]
	s_nop 7
	v_cvt_pk_bf16_f32 v176, v240, v241
	v_cvt_pk_bf16_f32 v177, v242, v243
	v_cvt_pk_bf16_f32 v184, v244, v245
	v_cvt_pk_bf16_f32 v185, v246, v247
	ds_write_b64 v127, v[176:177] offset:18432
	ds_write_b64 v129, v[184:185] offset:18432
	s_waitcnt lgkmcnt(0)
	s_barrier
	ds_read_b64 v[242:243], v127 offset:18432
	ds_read_b64 v[246:247], v129 offset:18432
	ds_read_b128 v[176:179], v173 offset:0
	ds_read_b128 v[224:227], v107 offset:18432
	ds_read_b128 v[184:187], v174 offset:0
	ds_read_b128 v[180:183], v173 offset:64
	ds_read_b128 v[228:231], v107 offset:18496
	ds_read_b128 v[188:191], v174 offset:64
	s_waitcnt lgkmcnt(7)
	v_lshlrev_b32_e32 v240, 16, v242
	v_and_b32_e32 v241, 0xffff0000, v242
	v_lshlrev_b32_e32 v242, 16, v243
	v_and_b32_e32 v243, 0xffff0000, v243
	s_waitcnt lgkmcnt(6)
	v_lshlrev_b32_e32 v244, 16, v246
	v_and_b32_e32 v245, 0xffff0000, v246
	v_lshlrev_b32_e32 v246, 16, v247
	v_and_b32_e32 v247, 0xffff0000, v247
	s_nop 1
	s_waitcnt lgkmcnt(4)
	v_mfma_f32_16x16x32_bf16 v[240:243], v[176:179], v[224:227], v[240:243]
	s_waitcnt lgkmcnt(3)
	v_mfma_f32_16x16x32_bf16 v[244:247], v[184:187], v[224:227], v[244:247]
	s_waitcnt lgkmcnt(1)
	v_mfma_f32_16x16x32_bf16 v[240:243], v[180:183], v[228:231], v[240:243]
	s_waitcnt lgkmcnt(0)
	v_mfma_f32_16x16x32_bf16 v[244:247], v[188:191], v[228:231], v[244:247]
	s_nop 7
	v_cvt_pk_bf16_f32 v176, v240, v241
	v_cvt_pk_bf16_f32 v177, v242, v243
	v_cvt_pk_bf16_f32 v184, v244, v245
	v_cvt_pk_bf16_f32 v185, v246, v247
	ds_write_b64 v97, v[176:177] offset:18432
	ds_write_b64 v98, v[184:185] offset:18432
	s_waitcnt lgkmcnt(0)
	s_barrier
	s_branch .La2_done
; __device__ __forceinline__ void st4_lds(LAS unsigned char* p, f32x4 v) { v2u w; w.x = pk2(v[0], v[1]); w.y = pk2(v[2], v[3]); *(LAS v2u*)p = w; }
; __device__ __forceinline__ f32x4 ld4_lds(const LAS unsigned char* p) { const v2u w = *(const LAS v2u*)p; return (f32x4){bflo(w.x), bfhi(w.x), bflo(w.y), bfhi(w.y)}; }
; #define LBAR() asm volatile("s_waitcnt lgkmcnt(0)\n\ts_barrier" ::: "memory")
; __device__ __forceinline__ void rwkv_chunk_group(Frame& F, int bc, unsigned long long& tsub) {
;     ...
;     for (int it = 0; it < 6; ++it) {
;         const int rM = (it & 1) ? L_AT : L_M, rMT = (it & 1) ? L_BT : L_MT, rTT = (it & 1) ? L_KT : L_TT;
;         const int wM = (it & 1) ? L_M : L_AT, wMT = (it & 1) ? L_MT : L_BT, wTT = (it & 1) ? L_TT : L_KT;
; #pragma unroll
;         for (int q = 0; q < 2; ++q) { const int tw = 2 * w + q, p0 = 16 * (tw >> 2), q0 = 16 * (tw & 3); const int o = (p0 + fr) * LD + (q0 + 4 * fq) * 2;
;             f32x4 tn = Z4, mn = Z4;
;             if (q0 <= p0) { tn = mm_tile(L + rM, LD, q0, L + rTT, LD, p0, 2, ld4_lds(L + rTT + o), fr, fq);
;                           }
;             if (q0 >= p0 && it < 5) mn = mm_tile(L + rMT, LD, q0, L + rM, LD, p0, 2, Z4, fr, fq);
;             st4_lds(L + wTT + o, tn); if (it < 5) { st4_lds(L + wM + o, mn); st4t_lds(L + wMT, p0 + fr, q0 + 4 * fq, mn); } }
;         LBAR();
;     }
.La2_FTFT:
	ds_read_b128 v[176:179], v175 offset:9216
	ds_read_b128 v[232:235], v132 offset:0
	ds_read_b128 v[184:187], v96 offset:9216
	ds_read_b128 v[180:183], v175 offset:9280
	ds_read_b128 v[236:239], v132 offset:64
	ds_read_b128 v[188:191], v96 offset:9280
	s_waitcnt lgkmcnt(4)
	v_mfma_f32_16x16x32_bf16 v[240:243], v[176:179], v[232:235], 0
	s_waitcnt lgkmcnt(3)
	v_mfma_f32_16x16x32_bf16 v[244:247], v[184:187], v[232:235], 0
	s_waitcnt lgkmcnt(1)
	v_mfma_f32_16x16x32_bf16 v[240:243], v[180:183], v[236:239], v[240:243]
	s_waitcnt lgkmcnt(0)
	v_mfma_f32_16x16x32_bf16 v[244:247], v[188:191], v[236:239], v[244:247]
	s_nop 7
	v_cvt_pk_bf16_f32 v176, v240, v241
	v_cvt_pk_bf16_f32 v177, v242, v243
	v_cvt_pk_bf16_f32 v184, v244, v245
	v_cvt_pk_bf16_f32 v185, v246, v247
	ds_write_b64 v127, v[102:103] offset:18432
	ds_write_b64 v127, v[176:177] offset:0
	ds_write_b16 v151, v176 offset:9216
	ds_write_b16_d16_hi v151, v176 offset:9360
	ds_write_b16 v151, v177 offset:9504
	ds_write_b16_d16_hi v151, v177 offset:9648
	ds_write_b64 v129, v[102:103] offset:18432
	ds_write_b64 v129, v[184:185] offset:0
	ds_write_b16 v152, v184 offset:9216
	ds_write_b16_d16_hi v152, v184 offset:9360
	ds_write_b16 v152, v185 offset:9504
	ds_write_b16_d16_hi v152, v185 offset:9648
	s_waitcnt lgkmcnt(0)
	s_barrier
	ds_read_b128 v[176:179], v173 offset:9216
	ds_read_b128 v[232:235], v107 offset:0
	ds_read_b128 v[184:187], v174 offset:9216
	ds_read_b128 v[180:183], v173 offset:9280
	ds_read_b128 v[236:239], v107 offset:64
	ds_read_b128 v[188:191], v174 offset:9280
	s_waitcnt lgkmcnt(4)
	v_mfma_f32_16x16x32_bf16 v[240:243], v[176:179], v[232:235], 0
	s_waitcnt lgkmcnt(3)
	v_mfma_f32_16x16x32_bf16 v[244:247], v[184:187], v[232:235], 0
	s_waitcnt lgkmcnt(1)
	v_mfma_f32_16x16x32_bf16 v[240:243], v[180:183], v[236:239], v[240:243]
	s_waitcnt lgkmcnt(0)
	v_mfma_f32_16x16x32_bf16 v[244:247], v[188:191], v[236:239], v[244:247]
	s_nop 7
	v_cvt_pk_bf16_f32 v176, v240, v241
	v_cvt_pk_bf16_f32 v177, v242, v243
	v_cvt_pk_bf16_f32 v184, v244, v245
	v_cvt_pk_bf16_f32 v185, v246, v247
	ds_write_b64 v97, v[176:177] offset:0
	ds_write_b16 v148, v176 offset:0
	ds_write_b16_d16_hi v148, v176 offset:144
	ds_write_b16 v148, v177 offset:288
	ds_write_b16_d16_hi v148, v177 offset:432
	ds_write_b64 v98, v[184:185] offset:0
	ds_write_b16 v149, v184 offset:0
	ds_write_b16_d16_hi v149, v184 offset:144
	ds_write_b16 v149, v185 offset:288
	ds_write_b16_d16_hi v149, v185 offset:432
	s_waitcnt lgkmcnt(0)
	s_barrier
	ds_read_b128 v[176:179], v175 offset:9216
	ds_read_b128 v[232:235], v132 offset:0
	ds_read_b128 v[184:187], v96 offset:9216
	ds_read_b128 v[180:183], v175 offset:9280
	ds_read_b128 v[236:239], v132 offset:64
	ds_read_b128 v[188:191], v96 offset:9280
	s_waitcnt lgkmcnt(4)
	v_mfma_f32_16x16x32_bf16 v[240:243], v[176:179], v[232:235], 0
	s_waitcnt lgkmcnt(3)
	v_mfma_f32_16x16x32_bf16 v[244:247], v[184:187], v[232:235], 0
	s_waitcnt lgkmcnt(1)
	v_mfma_f32_16x16x32_bf16 v[240:243], v[180:183], v[236:239], v[240:243]
	s_waitcnt lgkmcnt(0)
	v_mfma_f32_16x16x32_bf16 v[244:247], v[188:191], v[236:239], v[244:247]
	s_nop 7
	v_cvt_pk_bf16_f32 v176, v240, v241
	v_cvt_pk_bf16_f32 v177, v242, v243
	v_cvt_pk_bf16_f32 v184, v244, v245
	v_cvt_pk_bf16_f32 v185, v246, v247
	ds_write_b64 v127, v[176:177] offset:0
	ds_write_b16 v151, v176 offset:9216
	ds_write_b16_d16_hi v151, v176 offset:9360
	ds_write_b16 v151, v177 offset:9504
	ds_write_b16_d16_hi v151, v177 offset:9648
	ds_write_b64 v129, v[184:185] offset:0
	ds_write_b16 v152, v184 offset:9216
	ds_write_b16_d16_hi v152, v184 offset:9360
	ds_write_b16 v152, v185 offset:9504
	ds_write_b16_d16_hi v152, v185 offset:9648
	s_waitcnt lgkmcnt(0)
	s_barrier
	ds_read_b128 v[176:179], v173 offset:9216
	ds_read_b128 v[232:235], v107 offset:0
	ds_read_b128 v[184:187], v174 offset:9216
	ds_read_b128 v[180:183], v173 offset:9280
	ds_read_b128 v[236:239], v107 offset:64
	ds_read_b128 v[188:191], v174 offset:9280
	s_waitcnt lgkmcnt(4)
	v_mfma_f32_16x16x32_bf16 v[240:243], v[176:179], v[232:235], 0
	s_waitcnt lgkmcnt(3)
	v_mfma_f32_16x16x32_bf16 v[244:247], v[184:187], v[232:235], 0
	s_waitcnt lgkmcnt(1)
	v_mfma_f32_16x16x32_bf16 v[240:243], v[180:183], v[236:239], v[240:243]
	s_waitcnt lgkmcnt(0)
	v_mfma_f32_16x16x32_bf16 v[244:247], v[188:191], v[236:239], v[244:247]
	s_nop 7
	v_cvt_pk_bf16_f32 v176, v240, v241
	v_cvt_pk_bf16_f32 v177, v242, v243
	v_cvt_pk_bf16_f32 v184, v244, v245
	v_cvt_pk_bf16_f32 v185, v246, v247
	ds_write_b64 v97, v[176:177] offset:0
	ds_write_b16 v148, v176 offset:0
	ds_write_b16_d16_hi v148, v176 offset:144
	ds_write_b16 v148, v177 offset:288
	ds_write_b16_d16_hi v148, v177 offset:432
	ds_write_b64 v98, v[184:185] offset:0
	ds_write_b16 v149, v184 offset:0
	ds_write_b16_d16_hi v149, v184 offset:144
	ds_write_b16 v149, v185 offset:288
	ds_write_b16_d16_hi v149, v185 offset:432
	s_waitcnt lgkmcnt(0)
	s_barrier
	ds_read_b128 v[176:179], v175 offset:9216
	ds_read_b128 v[232:235], v132 offset:0
	ds_read_b128 v[184:187], v96 offset:9216
	ds_read_b128 v[180:183], v175 offset:9280
	ds_read_b128 v[236:239], v132 offset:64
	ds_read_b128 v[188:191], v96 offset:9280
	s_waitcnt lgkmcnt(4)
	v_mfma_f32_16x16x32_bf16 v[240:243], v[176:179], v[232:235], 0
	s_waitcnt lgkmcnt(3)
	v_mfma_f32_16x16x32_bf16 v[244:247], v[184:187], v[232:235], 0
	s_waitcnt lgkmcnt(1)
	v_mfma_f32_16x16x32_bf16 v[240:243], v[180:183], v[236:239], v[240:243]
	s_waitcnt lgkmcnt(0)
	v_mfma_f32_16x16x32_bf16 v[244:247], v[188:191], v[236:239], v[244:247]
	s_nop 7
	v_cvt_pk_bf16_f32 v176, v240, v241
	v_cvt_pk_bf16_f32 v177, v242, v243
	v_cvt_pk_bf16_f32 v184, v244, v245
	v_cvt_pk_bf16_f32 v185, v246, v247
	ds_write_b64 v127, v[176:177] offset:0
	ds_write_b16 v151, v176 offset:9216
	ds_write_b16_d16_hi v151, v176 offset:9360
	ds_write_b16 v151, v177 offset:9504
	ds_write_b16_d16_hi v151, v177 offset:9648
	ds_write_b64 v129, v[184:185] offset:0
	ds_write_b16 v152, v184 offset:9216
	ds_write_b16_d16_hi v152, v184 offset:9360
	ds_write_b16 v152, v185 offset:9504
	ds_write_b16_d16_hi v152, v185 offset:9648
	s_waitcnt lgkmcnt(0)
	s_barrier
	s_nop 7
	s_waitcnt lgkmcnt(0)
	s_barrier
